# attention: wait for the prefetched K/V tile at its consumer instead of inside every inner iteration
# speedup vs baseline: 1.0443x; 1.0115x over previous
.LBB0_461:
	s_lshl_b32 s73, s0, 7
	s_lshl_b64 s[28:29], s[66:67], 8
	v_lshl_add_u64 v[0:1], s[54:55], 0, v[160:161]
	v_lshlrev_b32_e32 v152, 1, v156
	s_and_b64 s[34:35], s[42:43], exec
	v_lshl_add_u64 v[0:1], v[0:1], 0, v[152:153]
	s_cselect_b32 s53, s53, s29
	s_cselect_b32 s52, s52, s28
	global_load_dwordx4 v[80:83], v[0:1], off
	v_mad_i64_i32 v[0:1], s[28:29], s72, v158, 0
	v_lshl_add_u64 v[188:189], v[0:1], 1, s[70:71]
	v_lshl_add_u32 v4, s1, 2, v171
	v_or_b32_e32 v184, s73, v173
	v_lshl_add_u64 v[0:1], v[188:189], 0, v[152:153]
	global_load_dwordx4 v[84:87], v[0:1], off
	v_or_b32_e32 v0, v184, v169
	v_mov_b32_e32 v1, v153
	v_lshlrev_b32_e32 v186, 6, v4
	v_lshl_add_u64 v[0:1], s[52:53], 0, v[0:1]
	v_ashrrev_i32_e32 v187, 31, v186
	v_lshl_add_u64 v[2:3], v[186:187], 1, v[162:163]
	v_lshlrev_b64 v[0:1], 11, v[0:1]
	v_lshl_add_u64 v[0:1], v[2:3], 0, v[0:1]
	v_add_u32_e32 v2, s7, v4
	v_ashrrev_i32_e32 v3, 31, v2
	s_mov_b32 s1, 0x10000
	global_load_dwordx4 v[96:99], v[0:1], off
	global_load_dwordx4 v[112:115], v[0:1], off offset:16
	global_load_dwordx4 v[100:103], v[0:1], off offset:32
	global_load_dwordx4 v[116:119], v[0:1], off offset:48
	v_lshl_add_u64 v[2:3], v[2:3], 2, s[50:51]
	v_add_co_u32_e32 v0, vcc, s1, v0
	global_load_dword v15, v[2:3], off
	s_nop 0
	v_addc_co_u32_e32 v1, vcc, 0, v1, vcc
	global_load_dwordx4 v[104:107], v[0:1], off
	global_load_dwordx4 v[88:91], v[0:1], off offset:16
	global_load_dwordx4 v[108:111], v[0:1], off offset:32
	global_load_dwordx4 v[92:95], v[0:1], off offset:48
	s_lshl_b64 s[28:29], s[66:67], 21
	s_lshl_b64 s[34:35], s[2:3], 13
	s_cmp_eq_u32 s0, 0
	s_cselect_b32 s38, 2, 0
	s_cmp_eq_u32 s0, 31
	s_cselect_b32 s0, 4, 6
	s_sub_i32 s0, s0, s38
	s_and_b64 s[36:37], s[42:43], exec
	s_cselect_b32 s0, s0, 0
	s_add_u32 s36, s33, s68
	s_addc_u32 s37, s74, s69
	s_add_u32 s28, s94, s28
	s_addc_u32 s29, s95, s29
	s_add_u32 s28, s28, s34
	s_addc_u32 s29, s29, s35
	s_lshl_b64 s[34:35], s[2:3], 1
	v_mov_b32_e32 v14, v153
	s_add_u32 s66, s36, s34
	v_mov_b32_e32 v0, v153
	v_mov_b32_e32 v1, v153
	v_mov_b32_e32 v2, v153
	v_mov_b32_e32 v3, v153
	v_mov_b32_e32 v4, v153
	v_mov_b32_e32 v5, v153
	v_mov_b32_e32 v6, v153
	v_mov_b32_e32 v7, v153
	v_mov_b32_e32 v8, v153
	v_mov_b32_e32 v9, v153
	v_mov_b32_e32 v10, v153
	v_mov_b32_e32 v11, v153
	v_mov_b32_e32 v12, v153
	v_mov_b32_e32 v13, v153
	s_addc_u32 s67, s37, s35
	s_add_i32 s78, s73, 0xffffff80
	s_mov_b32 s1, 0
	v_lshl_add_u64 v[190:191], s[28:29], 0, v[164:165]
	s_add_i32 s72, s76, s0
	s_sub_i32 s79, s38, s76
	v_add_u32_e32 v208, s78, v158
	v_mov_b32_e32 v185, 1.0
	v_mov_b32_e32 v207, 1.0
	s_waitcnt vmcnt(10)
	ds_write_b128 v175, v[80:83]
	s_waitcnt vmcnt(9)
	ds_write_b128 v175, v[84:87] offset:9216
	s_waitcnt lgkmcnt(0)
	s_barrier
	s_waitcnt vmcnt(0)
	v_mul_f32_e32 v213, 0x3fb8aa3b, v15
	v_mov_b32_e32 v15, v153
	v_mov_b64_e32 v[30:31], v[14:15]
	v_mov_b64_e32 v[46:47], v[14:15]
	v_mov_b64_e32 v[62:63], v[14:15]
	v_mov_b64_e32 v[28:29], v[12:13]
	v_mov_b64_e32 v[26:27], v[10:11]
	v_mov_b64_e32 v[24:25], v[8:9]
	v_mov_b64_e32 v[22:23], v[6:7]
	v_mov_b64_e32 v[20:21], v[4:5]
	v_mov_b64_e32 v[18:19], v[2:3]
	v_mov_b64_e32 v[16:17], v[0:1]
	v_mov_b64_e32 v[44:45], v[12:13]
	v_mov_b64_e32 v[42:43], v[10:11]
	v_mov_b64_e32 v[40:41], v[8:9]
	v_mov_b64_e32 v[38:39], v[6:7]
	v_mov_b64_e32 v[36:37], v[4:5]
	v_mov_b64_e32 v[34:35], v[2:3]
	v_mov_b64_e32 v[32:33], v[0:1]
	v_mov_b64_e32 v[60:61], v[12:13]
	v_mov_b64_e32 v[58:59], v[10:11]
	v_mov_b64_e32 v[56:57], v[8:9]
	v_mov_b64_e32 v[54:55], v[6:7]
	v_mov_b64_e32 v[52:53], v[4:5]
	v_mov_b64_e32 v[50:51], v[2:3]
	v_mov_b64_e32 v[48:49], v[0:1]
	v_mov_b32_e32 v210, v213

.LBB0_471:
	v_cvt_pk_bf16_f32 v64, v64, v65
	v_cvt_pk_bf16_f32 v65, v66, v67
	v_cvt_pk_bf16_f32 v66, v68, v69
	v_cvt_pk_bf16_f32 v67, v70, v71
	v_cvt_pk_bf16_f32 v68, v72, v73
	v_cvt_pk_bf16_f32 v69, v74, v75
	s_waitcnt lgkmcnt(3)
	v_mfma_f32_32x32x16_bf16 v[48:63], v[132:135], v[64:67], v[48:63]
	v_cvt_pk_bf16_f32 v70, v76, v77
	v_cvt_pk_bf16_f32 v71, v78, v79
	s_waitcnt lgkmcnt(1)
	v_mfma_f32_32x32x16_bf16 v[32:47], v[124:127], v[64:67], v[32:47]
	v_mfma_f32_32x32x16_bf16 v[48:63], v[128:131], v[68:71], v[48:63]
	s_waitcnt lgkmcnt(0)
	v_mfma_f32_32x32x16_bf16 v[32:47], v[120:123], v[68:71], v[32:47]
	v_mfma_f32_32x32x16_bf16 v[64:79], v[148:151], v[104:107], 0
	v_mfma_f32_32x32x16_bf16 v[64:79], v[144:147], v[88:91], v[64:79]
	v_mfma_f32_32x32x16_bf16 v[64:79], v[136:139], v[108:111], v[64:79]
	v_mfma_f32_32x32x16_bf16 v[64:79], v[140:143], v[92:95], v[64:79]
	s_nop 11
	v_max_f32_e32 v136, v65, v65
	v_max_f32_e32 v137, v64, v64
	v_max_f32_e32 v136, v137, v136
	v_max3_f32 v136, v136, v66, v67
	v_max3_f32 v136, v136, v68, v69
	v_max3_f32 v136, v136, v70, v71
	v_max3_f32 v136, v136, v72, v73
	v_max3_f32 v136, v136, v74, v75
	v_max3_f32 v136, v136, v76, v77
	v_max3_f32 v136, v136, v78, v79
	v_mov_b32_e32 v137, v136
	s_nop 1
	v_permlane32_swap_b32_e32 v136, v137
	v_max_f32_e32 v137, v137, v137
	v_max_f32_e32 v136, v136, v136
	v_max_f32_e32 v136, v136, v137
	v_mul_f32_e32 v136, 0x3e38aa3b, v136
	v_add_f32_e32 v137, 0x41000000, v213
	v_cmp_gt_f32_e32 vcc, v136, v137
	s_nop 1
	v_cndmask_b32_e32 v210, v213, v136, vcc
	v_fma_f32 v64, v64, s77, -v210
	v_exp_f32_e32 v64, v64
	v_fma_f32 v65, v65, s77, -v210
	v_exp_f32_e32 v65, v65
	v_fma_f32 v66, v66, s77, -v210
	v_exp_f32_e32 v66, v66
	v_fma_f32 v67, v67, s77, -v210
	v_exp_f32_e32 v67, v67
	v_fma_f32 v68, v68, s77, -v210
	v_add_f32_e32 v136, 0, v64
	v_exp_f32_e32 v68, v68
	v_fma_f32 v69, v69, s77, -v210
	v_add_f32_e32 v136, v65, v136
	v_exp_f32_e32 v69, v69
	v_fma_f32 v70, v70, s77, -v210
	v_add_f32_e32 v136, v66, v136
	v_exp_f32_e32 v70, v70
	v_fma_f32 v71, v71, s77, -v210
	v_add_f32_e32 v136, v67, v136
	v_exp_f32_e32 v71, v71
	v_fma_f32 v72, v72, s77, -v210
	v_add_f32_e32 v136, v68, v136
	v_exp_f32_e32 v72, v72
	v_fma_f32 v73, v73, s77, -v210
	v_add_f32_e32 v136, v69, v136
	v_exp_f32_e32 v73, v73
	v_fma_f32 v74, v74, s77, -v210
	v_add_f32_e32 v136, v70, v136
	v_exp_f32_e32 v74, v74
	v_fma_f32 v75, v75, s77, -v210
	v_add_f32_e32 v136, v71, v136
	v_exp_f32_e32 v75, v75
	v_fma_f32 v76, v76, s77, -v210
	v_add_f32_e32 v136, v72, v136
	v_exp_f32_e32 v76, v76
	v_fma_f32 v77, v77, s77, -v210
	v_add_f32_e32 v136, v73, v136
	v_exp_f32_e32 v77, v77
	v_fma_f32 v78, v78, s77, -v210
	v_add_f32_e32 v136, v74, v136
	v_exp_f32_e32 v78, v78
	v_fma_f32 v79, v79, s77, -v210
	v_add_f32_e32 v136, v75, v136
	v_exp_f32_e32 v79, v79
	v_add_f32_e32 v136, v76, v136
	v_add_f32_e32 v136, v77, v136
	v_add_f32_e32 v136, v78, v136
	v_add_f32_e32 v136, v79, v136
	v_mov_b32_e32 v137, v136
	s_nop 1
	v_permlane32_swap_b32_e32 v136, v137
	v_cmp_neq_f32_e32 vcc, v210, v213
	s_cbranch_vccz .LBB0_473
	v_sub_f32_e32 v138, v213, v210
	v_exp_f32_e32 v138, v138
	s_nop 0
	v_mul_f32_e32 v185, v185, v138
	v_pk_mul_f32 v[30:31], v[30:31], v[138:139] op_sel_hi:[1,0]
	v_pk_mul_f32 v[28:29], v[28:29], v[138:139] op_sel_hi:[1,0]
	v_pk_mul_f32 v[26:27], v[26:27], v[138:139] op_sel_hi:[1,0]
	v_pk_mul_f32 v[24:25], v[24:25], v[138:139] op_sel_hi:[1,0]
	v_pk_mul_f32 v[22:23], v[22:23], v[138:139] op_sel_hi:[1,0]
	v_pk_mul_f32 v[20:21], v[20:21], v[138:139] op_sel_hi:[1,0]
	v_pk_mul_f32 v[18:19], v[18:19], v[138:139] op_sel_hi:[1,0]
	v_pk_mul_f32 v[16:17], v[16:17], v[138:139] op_sel_hi:[1,0]
	v_pk_mul_f32 v[14:15], v[14:15], v[138:139] op_sel_hi:[1,0]
	v_pk_mul_f32 v[12:13], v[12:13], v[138:139] op_sel_hi:[1,0]
	v_pk_mul_f32 v[10:11], v[10:11], v[138:139] op_sel_hi:[1,0]
	v_pk_mul_f32 v[8:9], v[8:9], v[138:139] op_sel_hi:[1,0]
	v_pk_mul_f32 v[6:7], v[6:7], v[138:139] op_sel_hi:[1,0]
	v_pk_mul_f32 v[4:5], v[4:5], v[138:139] op_sel_hi:[1,0]
	v_pk_mul_f32 v[2:3], v[2:3], v[138:139] op_sel_hi:[1,0]
	v_pk_mul_f32 v[0:1], v[0:1], v[138:139] op_sel_hi:[1,0]

.LBB0_475:
	s_and_b64 vcc, exec, s[70:71]
	s_cbranch_vccz .LBB0_477
	s_bitcmp1_b32 s0, 0
	s_cselect_b32 s1, 0x4800, 0
	v_add_u32_e32 v64, s1, v175
	s_waitcnt vmcnt(1)
	ds_write_b128 v64, v[80:83]
	s_waitcnt vmcnt(0)
	ds_write_b128 v64, v[84:87] offset:9216
